# ConvGLU epilogue: boundary-row LDS publication rewritten without exec-mask branching (per-lane address, one mask, 16 ds_write_b128)
# speedup vs baseline: 1.0286x; 1.0025x over previous
; #define LAS __attribute__((address_space(3)))
;     __device__ __forceinline__ void run_glu(const f32x4 (&acc)[2][2][4][2], const pg8::Unit& u, int wr, int wc, int fr, int fq) const {
;         LAS float* B = (LAS float*)((LAS unsigned char*)0 + ldsb);
;         int fro = fr; asm volatile("" : "+v"(fro));
;         int lidx = (wc * 2) * 16 + fq * 4; asm volatile("" : "+v"(lidx));
; #pragma unroll
;         for (int ai = 0; ai < 2; ++ai)
; #pragma unroll
;             for (int m = 0; m < 4; ++m) { const int g = ai * 8 + wr * 4 + m;
; #pragma unroll
;                 for (int bj = 0; bj < 2; ++bj) {
;                     if (fr == 0) *(LAS f32x4*)(B + (g * 2 + 0) * 128 + lidx + bj * 16) = acc[ai][bj][m][0];
;                     if (fr == 15) *(LAS f32x4*)(B + (g * 2 + 1) * 128 + lidx + bj * 16) = acc[ai][bj][m][0];
;                 } }
;         asm volatile("s_waitcnt lgkmcnt(0)" ::: "memory"); __builtin_amdgcn_s_barrier(); asm volatile("" ::: "memory");
;         const int t17 = u.pm % 17; const bool tfirst = (t17 == 0) || (t17 == 1), tlast = (t17 == 0) || (t17 == 16);
; #pragma unroll
;         for (int bj = 0; bj < 2; ++bj) {
;             int col = u.pn * 256 + bj * 128 + wc * 32 + 8 * fq; asm volatile("" : "+v"(col)); const int ch = (col >> 3) * 4;
;             const f32x4 c0 = *(const f32x4*)(f0 + ch), c1 = *(const f32x4*)(f0 + DFF + ch), c2 = *(const f32x4*)(f0 + 2 * DFF + ch), cb = *(const f32x4*)(f1 + ch);
; #pragma unroll
;             for (int ai = 0; ai < 2; ++ai)
; #pragma unroll
;                 for (int m = 0; m < 4; ++m) { const int g = ai * 8 + wr * 4 + m;
;                     const int row = u.pm * 256 + g * 16 + fro;
;                     const f32x4 gt = acc[ai][bj][m][0], vl = acc[ai][bj][m][1];
;                     f32x4 gp, gn;
; #pragma unroll
;                     for (int i = 0; i < 4; ++i) { gp[i] = __int_as_float(__builtin_amdgcn_update_dpp(0, __float_as_int(gt[i]), 0x111, 0xF, 0xF, true));
;                                                   gn[i] = __int_as_float(__builtin_amdgcn_update_dpp(0, __float_as_int(gt[i]), 0x101, 0xF, 0xF, true)); }
;                     if (fr == 0) {
;                         if (g > 0) gp = *(const LAS f32x4*)(B + ((g - 1) * 2 + 1) * 128 + lidx + bj * 16);
.LBB0_329:
	s_cmp_lt_i32 s69, 3
	s_cbranch_scc1 .LBB0_653
	s_mov_b64 s[14:15], -1
	s_mov_b64 s[46:47], 0
	s_cmp_lt_i32 s69, 5
	s_mov_b64 s[2:3], 0
	s_cbranch_scc1 .LBB0_648
	s_cmp_eq_u32 s69, 5
	s_mov_b64 s[2:3], -1
	s_cbranch_scc0 .LBB0_645
	v_mov_b32_e32 v189, v211
	v_mov_b32_e32 v186, v214
	s_mov_b64 s[18:19], exec
	v_readlane_b32 s2, v255, 27
	v_lshlrev_b32_e32 v130, 2, v186
	v_cmp_eq_u32_e64 s[14:15], 0, v211
	v_cmp_eq_u32_e64 s[16:17], 15, v211
	v_mov_b32_e32 v96, 0x200
	v_add_u32_e32 v188, s2, v130
	v_cndmask_b32_e64 v131, 0, v96, s[16:17]
	s_or_b64 s[14:15], s[14:15], s[16:17]
	v_add_u32_e32 v96, v188, v131
	s_mov_b64 exec, s[14:15]
	ds_write_b128 v96, v[126:129]
	ds_write_b128 v96, v[118:121] offset:64
	s_mov_b64 exec, s[18:19]
	v_readlane_b32 s2, v255, 29
	s_nop 1
	v_lshl_add_u32 v222, v186, 2, s2
	v_add_u32_e32 v130, v222, v131
	s_mov_b64 exec, s[14:15]
	ds_write_b128 v130, v[110:113]
	ds_write_b128 v130, v[102:105] offset:64
	s_mov_b64 exec, s[18:19]
	v_readlane_b32 s2, v255, 31
	s_nop 1
	v_lshl_add_u32 v221, v186, 2, s2
	v_add_u32_e32 v96, v221, v131
	s_mov_b64 exec, s[14:15]
	ds_write_b128 v96, v[92:95]
	ds_write_b128 v96, v[84:87] offset:64
	s_mov_b64 exec, s[18:19]
	v_readlane_b32 s2, v255, 34
	s_nop 1
	v_lshl_add_u32 v220, v186, 2, s2
	v_add_u32_e32 v130, v220, v131
	s_mov_b64 exec, s[14:15]
	ds_write_b128 v130, v[76:79]
	ds_write_b128 v130, v[68:71] offset:64
	s_mov_b64 exec, s[18:19]
	v_readlane_b32 s2, v255, 36
	s_nop 1
	v_lshl_add_u32 v219, v186, 2, s2
	v_add_u32_e32 v96, v219, v131
	s_mov_b64 exec, s[14:15]
	ds_write_b128 v96, v[60:63]
	ds_write_b128 v96, v[52:55] offset:64
	s_mov_b64 exec, s[18:19]
	v_readlane_b32 s2, v255, 38
	s_nop 1
	v_lshl_add_u32 v218, v186, 2, s2
	v_add_u32_e32 v130, v218, v131
	s_mov_b64 exec, s[14:15]
	ds_write_b128 v130, v[44:47]
	ds_write_b128 v130, v[36:39] offset:64
	s_mov_b64 exec, s[18:19]
	v_readlane_b32 s2, v255, 40
	s_nop 1
	v_lshl_add_u32 v217, v186, 2, s2
	v_add_u32_e32 v96, v217, v131
	s_mov_b64 exec, s[14:15]
	ds_write_b128 v96, v[28:31]
	ds_write_b128 v96, v[20:23] offset:64
	s_mov_b64 exec, s[18:19]
	v_readlane_b32 s2, v255, 42
	s_nop 1
	v_lshl_add_u32 v96, v186, 2, s2
	v_add_u32_e32 v130, v96, v131
	s_mov_b64 exec, s[14:15]
	ds_write_b128 v130, v[12:15]
	ds_write_b128 v130, v[4:7] offset:64
	s_mov_b64 exec, s[18:19]
	v_lshl_or_b32 v223, s4, 8, v215
	v_mov_b32_e32 v182, v223
	s_waitcnt lgkmcnt(0)
	s_barrier
	v_readlane_b32 s2, v255, 23
	v_ashrrev_i32_e32 v130, 1, v182
	v_and_b32_e32 v166, -4, v130
	v_ashrrev_i32_e32 v167, 31, v166
	v_lshlrev_b64 v[142:143], 2, v[166:167]
	v_readlane_b32 s3, v255, 24
	v_lshl_add_u64 v[130:131], s[70:71], 0, v[142:143]
	v_ashrrev_i32_e32 v183, 31, v182
	v_lshl_add_u64 v[134:135], s[2:3], 0, v[142:143]
	v_readlane_b32 s2, v255, 25
	v_readlane_b32 s3, v255, 26
	global_load_dwordx4 v[130:133], v[130:131], off
	s_nop 0
	global_load_dwordx4 v[134:137], v[134:135], off
	v_lshl_add_u64 v[138:139], s[2:3], 0, v[142:143]
	v_readlane_b32 s2, v254, 38
	v_readlane_b32 s3, v254, 39
	global_load_dwordx4 v[138:141], v[138:139], off
	v_mov_b32_dpp v146, v126 row_shr:1 row_mask:0xf bank_mask:0xf bound_ctrl:1
	v_lshl_add_u64 v[142:143], s[2:3], 0, v[142:143]
	global_load_dwordx4 v[142:145], v[142:143], off
	s_mul_hi_i32 s2, s5, 0x78787879
	s_lshr_b32 s3, s2, 31
	s_ashr_i32 s2, s2, 3
	s_add_i32 s2, s2, s3
	s_mul_i32 s2, s2, 17
	s_sub_i32 s16, s5, s2
	s_cmp_gt_u32 s16, 1
	s_cselect_b64 s[94:95], -1, 0
	v_mov_b32_dpp v171, v126 row_shl:1 row_mask:0xf bank_mask:0xf bound_ctrl:1
	v_mov_b32_dpp v147, v127 row_shr:1 row_mask:0xf bank_mask:0xf bound_ctrl:1
	v_mov_b32_dpp v151, v127 row_shl:1 row_mask:0xf bank_mask:0xf bound_ctrl:1
	v_mov_b32_dpp v148, v128 row_shr:1 row_mask:0xf bank_mask:0xf bound_ctrl:1
	v_mov_b32_dpp v169, v128 row_shl:1 row_mask:0xf bank_mask:0xf bound_ctrl:1
	v_mov_b32_dpp v149, v129 row_shr:1 row_mask:0xf bank_mask:0xf bound_ctrl:1
	v_mov_b32_dpp v153, v129 row_shl:1 row_mask:0xf bank_mask:0xf bound_ctrl:1
	s_mov_b64 s[2:3], exec
	v_readlane_b32 s14, v255, 44
	v_readlane_b32 s15, v255, 45
	s_and_b64 s[14:15], s[2:3], s[14:15]
	s_mov_b64 exec, s[14:15]
	s_cbranch_execz .LBB0_443
	v_readlane_b32 s18, v254, 51
	v_readlane_b32 s19, v254, 52
	s_mov_b64 s[14:15], -1
	s_and_b64 vcc, exec, s[18:19]
	s_cbranch_vccz .LBB0_441
	v_mov_b32_e32 v149, 0
	s_andn2_b64 vcc, exec, s[94:95]
	v_mov_b32_e32 v148, 0
	v_mov_b32_e32 v147, 0
	v_mov_b32_e32 v146, 0
	s_cbranch_vccnz .LBB0_440
	s_lshl_b32 s14, s5, 1
	s_add_i32 s14, s14, -2
	s_mul_hi_i32 s15, s14, 0x2c00
	s_mulk_i32 s14, 0x2c00
	v_readlane_b32 s18, v254, 36
	v_readlane_b32 s19, v254, 37
	s_add_u32 s14, s18, s14
	s_addc_u32 s15, s19, s15
	v_lshl_add_u64 v[146:147], v[182:183], 1, s[14:15]
	global_load_dwordx2 v[148:149], v[146:147], off
	s_waitcnt vmcnt(0)
	v_lshlrev_b32_e32 v146, 16, v148
	v_and_b32_e32 v147, 0xffff0000, v148
	v_lshlrev_b32_e32 v148, 16, v149
	v_and_b32_e32 v149, 0xffff0000, v149
